# PH5 attention pair combine: partner partials read with sc1 loads, acquire invalidate removed
# speedup vs baseline: 1.0012x; 1.0012x over previous
.LBB0_2221:
	s_mov_b64 s[10:11], 0
	s_cbranch_execnz .LBB0_2226
	s_branch .LBB0_2229
.LBB0_2222:
	s_waitcnt vmcnt(0)
.LBB0_2223:
	s_or_b64 exec, exec, s[10:11]
	s_barrier
	s_and_saveexec_b64 s[10:11], s[4:5]
	s_cbranch_execz .LBB0_2225
	global_load_dword v64, v[96:97], off sc1
	global_load_dword v65, v[96:97], off offset:256 sc1
	v_max_f32_e32 v66, v176, v176
	s_waitcnt vmcnt(1)
	v_max_f32_e32 v67, v64, v64
	v_max_f32_e32 v66, v66, v67
	v_sub_f32_e32 v64, v64, v66
	v_sub_f32_e32 v67, v176, v66
	v_mul_f32_e32 v64, 0x3dd53b94, v64
	v_mul_f32_e32 v66, 0x3dd53b94, v67
	v_exp_f32_e32 v64, v64
	v_exp_f32_e32 v66, v66
	s_waitcnt vmcnt(0)
	v_mul_f32_e32 v65, v65, v64
	v_fmac_f32_e32 v65, v175, v66
	v_rcp_f32_e32 v65, v65
	s_nop 0
	v_mul_f32_e32 v66, v66, v65
	v_mul_f32_e32 v64, v64, v65
	ds_write2_b32 v174, v66, v64 offset1:32
.LBB0_2225:
	s_or_b64 exec, exec, s[10:11]
	v_add_co_u32_e32 v84, vcc, 0x1000, v94
	s_waitcnt lgkmcnt(0)
	global_load_dwordx4 v[72:75], v[94:95], off sc1
	s_nop 0
	v_addc_co_u32_e32 v85, vcc, 0, v95, vcc
	v_add_co_u32_e32 v92, vcc, 0x2000, v94
	global_load_dwordx4 v[76:79], v[84:85], off sc1
	s_nop 0
	v_addc_co_u32_e32 v93, vcc, 0, v95, vcc
	v_add_co_u32_e32 v118, vcc, 0x3000, v94
	global_load_dwordx4 v[80:83], v[92:93], off sc1
	s_nop 0
	v_addc_co_u32_e32 v119, vcc, 0, v95, vcc
	global_load_dwordx4 v[86:89], v[118:119], off sc1
	v_lshl_add_u32 v156, v171, 4, v137
	ds_read_b128 v[68:71], v156
	ds_read_b128 v[64:67], v156 offset:32
	ds_read_b128 v[108:111], v156 offset:128
	s_mov_b64 s[10:11], -1
	s_waitcnt vmcnt(3) lgkmcnt(0)
	v_pk_mul_f32 v[106:107], v[72:73], v[108:109]
	v_pk_mul_f32 v[100:101], v[74:75], v[110:111]
	s_waitcnt vmcnt(2)
	v_pk_mul_f32 v[98:99], v[108:109], v[76:77]
	v_pk_mul_f32 v[104:105], v[110:111], v[78:79]
	s_waitcnt vmcnt(1)
	v_pk_mul_f32 v[102:103], v[108:109], v[80:81]
	s_waitcnt vmcnt(0)
	v_pk_mul_f32 v[138:139], v[108:109], v[86:87]
	v_pk_mul_f32 v[108:109], v[110:111], v[82:83]
	v_pk_mul_f32 v[140:141], v[110:111], v[88:89]
	global_load_dwordx4 v[72:75], v[94:95], off offset:1024 sc1
	global_load_dwordx4 v[76:79], v[84:85], off offset:1024 sc1
	global_load_dwordx4 v[80:83], v[92:93], off offset:1024 sc1
	global_load_dwordx4 v[86:89], v[118:119], off offset:1024 sc1
	ds_read_b128 v[120:123], v156 offset:160
	v_pk_fma_f32 v[138:139], v[16:17], v[68:69], v[138:139]
	s_waitcnt vmcnt(3) lgkmcnt(0)
	v_pk_mul_f32 v[112:113], v[72:73], v[120:121]
	s_waitcnt vmcnt(2)
	v_pk_mul_f32 v[110:111], v[120:121], v[76:77]
	s_waitcnt vmcnt(1)
	v_pk_mul_f32 v[114:115], v[120:121], v[80:81]
	s_waitcnt vmcnt(0)
	v_pk_mul_f32 v[142:143], v[120:121], v[86:87]
	v_pk_mul_f32 v[116:117], v[122:123], v[78:79]
	v_pk_mul_f32 v[146:147], v[122:123], v[82:83]
	v_pk_mul_f32 v[144:145], v[122:123], v[88:89]
	global_load_dwordx4 v[76:79], v[94:95], off offset:2048 sc1
	global_load_dwordx4 v[80:83], v[84:85], off offset:2048 sc1
	global_load_dwordx4 v[86:89], v[92:93], off offset:2048 sc1
	global_load_dwordx4 v[126:129], v[118:119], off offset:2048 sc1
	v_pk_mul_f32 v[120:121], v[74:75], v[122:123]
	ds_read_b128 v[72:75], v156 offset:64
	ds_read_b128 v[132:135], v156 offset:192
	v_pk_fma_f32 v[116:117], v[54:55], v[66:67], v[116:117]
	global_load_dwordx4 v[178:181], v[118:119], off offset:3072 sc1
	v_pk_fma_f32 v[118:119], v[4:5], v[64:65], v[112:113]
	v_pk_fma_f32 v[112:113], v[6:7], v[66:67], v[120:121]
	v_pk_fma_f32 v[120:121], v[36:37], v[64:65], v[114:115]
	v_pk_fma_f32 v[114:115], v[38:39], v[66:67], v[146:147]
	s_waitcnt vmcnt(4) lgkmcnt(0)
	v_pk_mul_f32 v[122:123], v[76:77], v[132:133]
	s_waitcnt vmcnt(3)
	v_pk_mul_f32 v[124:125], v[132:133], v[80:81]
	s_waitcnt vmcnt(2)
	v_pk_mul_f32 v[154:155], v[134:135], v[88:89]
	global_load_dwordx4 v[88:91], v[94:95], off offset:3072 sc1
	v_pk_mul_f32 v[152:153], v[132:133], v[86:87]
	s_waitcnt vmcnt(2)
	v_pk_mul_f32 v[148:149], v[132:133], v[126:127]
	v_pk_mul_f32 v[130:131], v[78:79], v[134:135]
	v_pk_mul_f32 v[132:133], v[134:135], v[82:83]
	ds_read_b128 v[76:79], v156 offset:96
	ds_read_b128 v[80:83], v156 offset:224
	v_pk_mul_f32 v[150:151], v[134:135], v[128:129]
	v_pk_fma_f32 v[128:129], v[2:3], v[70:71], v[100:101]
	v_pk_fma_f32 v[100:101], v[10:11], v[74:75], v[130:131]
	s_waitcnt lgkmcnt(1)
	v_mov_b32_e32 v156, v79
	s_waitcnt lgkmcnt(0)
	v_mov_b32_e32 v157, v83
	v_pk_fma_f32 v[130:131], v[50:51], v[70:71], v[104:105]
	v_pk_fma_f32 v[104:105], v[58:59], v[74:75], v[132:133]
	v_pk_fma_f32 v[132:133], v[32:33], v[68:69], v[102:103]
	v_pk_fma_f32 v[102:103], v[42:43], v[74:75], v[154:155]
	v_mul_f32_e32 v134, v14, v78
	v_mul_f32_e32 v162, v62, v78
	v_mul_f32_e32 v166, v46, v78
	v_pk_fma_f32 v[126:127], v[0:1], v[68:69], v[106:107]
	v_pk_fma_f32 v[106:107], v[8:9], v[72:73], v[122:123]
	v_pk_fma_f32 v[122:123], v[52:53], v[64:65], v[110:111]
	v_pk_fma_f32 v[110:111], v[56:57], v[72:73], v[124:125]
	v_pk_fma_f32 v[124:125], v[34:35], v[70:71], v[108:109]
	v_pk_fma_f32 v[108:109], v[40:41], v[72:73], v[152:153]
	v_mul_f32_e32 v152, v30, v78
	s_waitcnt vmcnt(1)
	v_mul_f32_e32 v154, v82, v180
	v_mov_b32_e32 v180, v31
	v_pk_mul_f32 v[146:147], v[80:81], v[178:179]
	v_pk_mul_f32 v[78:79], v[180:181], v[156:157]
	s_waitcnt vmcnt(0)
	v_mul_f32_e32 v158, v90, v82
	v_mov_b32_e32 v90, v15
	v_pk_mul_f32 v[86:87], v[90:91], v[156:157]
	global_load_dwordx4 v[90:93], v[92:93], off offset:3072 sc1
	v_mov_b32_e32 v135, v86
	v_mov_b32_e32 v159, v87
	global_load_dwordx4 v[84:87], v[84:85], off offset:3072 sc1
	v_mov_b32_e32 v153, v78
	v_mov_b32_e32 v155, v79
	v_pk_fma_f32 v[78:79], v[22:23], v[66:67], v[144:145]
	v_pk_fma_f32 v[66:67], v[28:29], v[76:77], v[146:147]
	s_waitcnt vmcnt(1)
	v_mul_f32_e32 v168, v82, v92
	v_mov_b32_e32 v92, v47
	s_waitcnt vmcnt(0)
	v_mul_f32_e32 v164, v82, v86
	v_mov_b32_e32 v86, v63
	v_pk_mul_f32 v[86:87], v[86:87], v[156:157]
	v_pk_mul_f32 v[84:85], v[80:81], v[84:85]
	v_mov_b32_e32 v163, v86
	v_mov_b32_e32 v165, v87
	v_pk_mul_f32 v[86:87], v[92:93], v[156:157]
	v_pk_fma_f32 v[82:83], v[18:19], v[70:71], v[140:141]
	v_mov_b32_e32 v167, v86
	v_mov_b32_e32 v169, v87
	v_pk_mul_f32 v[86:87], v[88:89], v[80:81]
	v_pk_add_f32 v[88:89], v[162:163], v[164:165]
	v_pk_fma_f32 v[92:93], v[12:13], v[76:77], v[86:87]
	v_pk_add_f32 v[86:87], v[134:135], v[158:159]
	v_pk_fma_f32 v[134:135], v[48:49], v[68:69], v[98:99]
	v_pk_fma_f32 v[98:99], v[60:61], v[76:77], v[84:85]
	v_pk_mul_f32 v[84:85], v[80:81], v[90:91]
	v_pk_fma_f32 v[80:81], v[20:21], v[64:65], v[142:143]
	v_pk_fma_f32 v[90:91], v[44:45], v[76:77], v[84:85]
	v_pk_add_f32 v[84:85], v[166:167], v[168:169]
	v_pk_fma_f32 v[70:71], v[24:25], v[72:73], v[148:149]
	v_pk_fma_f32 v[68:69], v[26:27], v[74:75], v[150:151]
	v_pk_add_f32 v[64:65], v[152:153], v[154:155]
	s_branch .LBB0_2229
